# MLA QK^T: all 12 K-fragment LDS reads issued up front into dead registers, counted lgkmcnt waits (on top of O-copy removal)
# speedup vs baseline: 1.0183x; 1.0047x over previous
; #define MFMA32(a, b, c) __builtin_amdgcn_mfma_f32_32x32x16_bf16((a), (b), (c), 0, 0, 0)
; #define AT_SB __builtin_amdgcn_sched_barrier(0);
; template <int DQK, int MODE, bool QN, bool KN> ...
;     ...
;   auto compute = [&](int it, int bufi) {
;     const int kt = tile_of(it);
;     const int koff = (kt & 1) * 64;
;     const char* sK = smem + bufi * BUF + koff * KROW;
;     const char* sV = smem + bufi * BUF + KBYTES + koff * 64;
;     bool active = (MODE == 0) || (kt * 64 <= qwmax);
;     if (MODE == 2 && active) active = __builtin_amdgcn_ballot_w64(carry >= 1.17549435e-38f) != 0;
;     if (active) {
;       f32x16 sacc[2];
;       const float sinit = fixed_shift ? -sbound : 0.f;
; #pragma unroll
;       for (int kb = 0; kb < 2; ++kb) {
; #pragma unroll
;         for (int i = 0; i < 16; ++i) sacc[kb][i] = sinit;
; #pragma unroll
;         for (int s = 0; s < NS; ++s) {
;           const bf16x8 kf = *(const bf16x8*)(sK + (kb * 32 + r) * KROW + s * 32 + h * 16);
;           sacc[kb] = MFMA32(kf, qf[s], sacc[kb]);
;         }
;       }
;       const bool diag = (MODE != 0) && (kt * 64 + 63 >= q0 + wave * 32);
;       if (MODE != 0 && diag) {
; #pragma unroll
;         for (int kb = 0; kb < 2; ++kb)
; #pragma unroll
;           for (int i = 0; i < 16; ++i) {
;             const int key = kt * 64 + kb * 32 + (i & 3) + 8 * (i >> 2) + 4 * h;
;             if (MODE == 1 ? (key > qrow) : (key >= qrow)) sacc[kb][i] = -INFINITY;
;           }
;       }
;     ...
;     AT_SB AT_GLOAD(rk0, rv0, sg + 2)
.LBB0_1198:
	s_add_i32 s55, s45, -1
	s_min_i32 s2, s55, s13
	s_lshl_b32 s4, s2, 7
	v_add_u32_e32 v0, s4, v238
	v_mad_i64_i32 v[2:3], s[2:3], v0, s36, v[220:221]
	v_add_u32_e32 v0, s4, v239
	v_mad_i64_i32 v[6:7], s[2:3], v0, s36, v[222:223]
	v_add_u32_e32 v0, s4, v240
	v_mad_i64_i32 v[10:11], s[2:3], v0, s36, v[224:225]
	v_add_u32_e32 v0, s4, v241
	v_mad_i64_i32 v[14:15], s[2:3], v0, s37, v[218:219]
	v_add_u32_e32 v0, s4, v242
	global_load_dwordx4 v[2:5], v[2:3], off
	s_nop 0
	global_load_dwordx4 v[6:9], v[6:7], off
	s_nop 0
	global_load_dwordx4 v[10:13], v[10:11], off
	s_nop 0
	global_load_dwordx4 v[204:207], v[14:15], off
	v_mad_i64_i32 v[14:15], s[2:3], v0, s37, v[218:219]
	global_load_dwordx4 v[208:211], v[14:15], off
	s_add_i32 s2, s53, 0xffffff01
	v_cmp_le_i32_e32 vcc, s2, v243
	s_and_saveexec_b64 s[2:3], vcc
	s_cbranch_execz .LBB0_1208
	ds_read_b128 v[32:35], v251
	ds_read_b128 v[36:39], v251 offset:32
	ds_read_b128 v[40:43], v251 offset:64
	ds_read_b128 v[44:47], v251 offset:96
	ds_read_b128 v[48:51], v251 offset:128
	ds_read_b128 v[52:55], v251 offset:160
	ds_read_b128 v[112:115], v251 offset:6656
	ds_read_b128 v[116:119], v251 offset:6688
	ds_read_b128 v[120:123], v251 offset:6720
	ds_read_b128 v[124:127], v251 offset:6752
	ds_read_b128 v[144:147], v251 offset:6784
	ds_read_b128 v[148:151], v251 offset:6816
	s_add_i32 s4, s53, 0xffffff40
	v_cmp_ge_i32_e32 vcc, s4, v236
	s_waitcnt lgkmcnt(11)
	v_mfma_f32_32x32x16_bf16 v[80:95], v[32:35], v[160:163], v[16:31]
	s_waitcnt lgkmcnt(10)
	v_mfma_f32_32x32x16_bf16 v[80:95], v[36:39], v[164:167], v[80:95]
	s_waitcnt lgkmcnt(9)
	v_mfma_f32_32x32x16_bf16 v[80:95], v[40:43], v[168:171], v[80:95]
	s_waitcnt lgkmcnt(8)
	v_mfma_f32_32x32x16_bf16 v[80:95], v[44:47], v[172:175], v[80:95]
	s_waitcnt lgkmcnt(7)
	v_mfma_f32_32x32x16_bf16 v[80:95], v[48:51], v[176:179], v[80:95]
	s_waitcnt lgkmcnt(6)
	v_mfma_f32_32x32x16_bf16 v[80:95], v[52:55], v[180:183], v[80:95]
	s_waitcnt lgkmcnt(5)
	v_mfma_f32_32x32x16_bf16 v[64:79], v[112:115], v[160:163], v[16:31]
	s_waitcnt lgkmcnt(4)
	v_mfma_f32_32x32x16_bf16 v[64:79], v[116:119], v[164:167], v[64:79]
	s_waitcnt lgkmcnt(3)
	v_mfma_f32_32x32x16_bf16 v[64:79], v[120:123], v[168:171], v[64:79]
	s_waitcnt lgkmcnt(2)
	v_mfma_f32_32x32x16_bf16 v[64:79], v[124:127], v[172:175], v[64:79]
	s_waitcnt lgkmcnt(1)
	v_mfma_f32_32x32x16_bf16 v[64:79], v[144:147], v[176:179], v[64:79]
	s_waitcnt lgkmcnt(0)
	v_mfma_f32_32x32x16_bf16 v[64:79], v[148:151], v[180:183], v[64:79]
	s_and_saveexec_b64 s[10:11], vcc
	s_cbranch_execz .LBB0_1201
	v_add_u32_e32 v0, s53, v247
	v_add_u32_e32 v14, 0xffffff01, v0
	v_cmp_lt_i32_e32 vcc, v14, v237
	s_nop 1
	v_cndmask_b32_e32 v81, v234, v81, vcc
	v_cmp_le_i32_e32 vcc, v14, v237
	v_add_u32_e32 v14, 0xffffff03, v0
	s_nop 0
	v_cndmask_b32_e32 v80, v234, v80, vcc
	v_cmp_le_i32_e32 vcc, v14, v237
	v_add_u32_e32 v14, 0xffffff04, v0
	s_nop 0
	v_cndmask_b32_e32 v82, v234, v82, vcc
	v_cmp_le_i32_e32 vcc, v14, v237
	v_add_u32_e32 v14, 0xffffff09, v0
	s_nop 0
	v_cndmask_b32_e32 v83, v234, v83, vcc
	v_cmp_le_i32_e32 vcc, v14, v237
	v_add_u32_e32 v14, 0xffffff0a, v0
	s_nop 0
	v_cndmask_b32_e32 v84, v234, v84, vcc
	v_cmp_le_i32_e32 vcc, v14, v237
	v_add_u32_e32 v14, 0xffffff0b, v0
	s_nop 0
	v_cndmask_b32_e32 v85, v234, v85, vcc
	v_cmp_le_i32_e32 vcc, v14, v237
	v_add_u32_e32 v14, 0xffffff0c, v0
	s_nop 0
	v_cndmask_b32_e32 v86, v234, v86, vcc
	v_cmp_le_i32_e32 vcc, v14, v237
	v_add_u32_e32 v14, 0xffffff11, v0
	s_nop 0
	v_cndmask_b32_e32 v87, v234, v87, vcc
	v_cmp_le_i32_e32 vcc, v14, v237
	v_add_u32_e32 v14, 0xffffff12, v0
	s_nop 0
	v_cndmask_b32_e32 v88, v234, v88, vcc
	v_cmp_le_i32_e32 vcc, v14, v237
	v_add_u32_e32 v14, 0xffffff13, v0
	s_nop 0
	v_cndmask_b32_e32 v89, v234, v89, vcc
	v_cmp_le_i32_e32 vcc, v14, v237
	v_add_u32_e32 v14, 0xffffff14, v0
	s_nop 0
	v_cndmask_b32_e32 v90, v234, v90, vcc
	v_cmp_le_i32_e32 vcc, v14, v237
	v_add_u32_e32 v14, 0xffffff19, v0
	s_nop 0
	v_cndmask_b32_e32 v91, v234, v91, vcc
	v_cmp_le_i32_e32 vcc, v14, v237
	v_add_u32_e32 v14, 0xffffff1a, v0
	s_nop 0
	v_cndmask_b32_e32 v92, v234, v92, vcc
	v_cmp_le_i32_e32 vcc, v14, v237
	v_add_u32_e32 v14, 0xffffff1b, v0
	s_nop 0
	v_cndmask_b32_e32 v93, v234, v93, vcc
	v_cmp_le_i32_e32 vcc, v14, v237
	v_add_u32_e32 v14, 0xffffff1c, v0
	s_nop 0
	v_cndmask_b32_e32 v94, v234, v94, vcc
	v_cmp_le_i32_e32 vcc, v14, v237
	v_add_u32_e32 v14, 0xffffff21, v0
	s_nop 0
	v_cndmask_b32_e32 v95, v234, v95, vcc
	v_cmp_le_i32_e32 vcc, v14, v237
	v_add_u32_e32 v14, 0xffffff22, v0
	s_nop 0
	v_cndmask_b32_e32 v64, v234, v64, vcc
	v_cmp_le_i32_e32 vcc, v14, v237
	v_add_u32_e32 v14, 0xffffff23, v0
	s_nop 0
	v_cndmask_b32_e32 v65, v234, v65, vcc
	v_cmp_le_i32_e32 vcc, v14, v237
	v_add_u32_e32 v14, 0xffffff24, v0
	s_nop 0
	v_cndmask_b32_e32 v66, v234, v66, vcc
	v_cmp_le_i32_e32 vcc, v14, v237
	v_add_u32_e32 v14, 0xffffff29, v0
	s_nop 0
	v_cndmask_b32_e32 v67, v234, v67, vcc
	v_cmp_le_i32_e32 vcc, v14, v237
	v_add_u32_e32 v14, 0xffffff2a, v0
	s_nop 0
	v_cndmask_b32_e32 v68, v234, v68, vcc
	v_cmp_le_i32_e32 vcc, v14, v237
	v_add_u32_e32 v14, 0xffffff2b, v0
	s_nop 0
	v_cndmask_b32_e32 v69, v234, v69, vcc
	v_cmp_le_i32_e32 vcc, v14, v237
	v_add_u32_e32 v14, 0xffffff2c, v0
	s_nop 0
	v_cndmask_b32_e32 v70, v234, v70, vcc
	v_cmp_le_i32_e32 vcc, v14, v237
	v_add_u32_e32 v14, 0xffffff31, v0
	s_nop 0
	v_cndmask_b32_e32 v71, v234, v71, vcc
	v_cmp_le_i32_e32 vcc, v14, v237
	v_add_u32_e32 v14, 0xffffff32, v0
	s_nop 0
	v_cndmask_b32_e32 v72, v234, v72, vcc
	v_cmp_le_i32_e32 vcc, v14, v237
	v_add_u32_e32 v14, 0xffffff33, v0
	s_nop 0
	v_cndmask_b32_e32 v73, v234, v73, vcc
	v_cmp_le_i32_e32 vcc, v14, v237
	v_add_u32_e32 v14, 0xffffff34, v0
	s_nop 0
	v_cndmask_b32_e32 v74, v234, v74, vcc
	v_cmp_le_i32_e32 vcc, v14, v237
	v_add_u32_e32 v14, 0xffffff39, v0
	s_nop 0
	v_cndmask_b32_e32 v75, v234, v75, vcc
	v_cmp_le_i32_e32 vcc, v14, v237
	v_add_u32_e32 v14, 0xffffff3a, v0
	s_nop 0
	v_cndmask_b32_e32 v76, v234, v76, vcc
	v_cmp_le_i32_e32 vcc, v14, v237
	v_add_u32_e32 v14, 0xffffff3b, v0
	v_add_u32_e32 v0, 0xffffff3c, v0
	v_cndmask_b32_e32 v77, v234, v77, vcc
	v_cmp_le_i32_e32 vcc, v14, v237
	s_nop 1
	v_cndmask_b32_e32 v78, v234, v78, vcc
	v_cmp_le_i32_e32 vcc, v0, v237
	s_nop 1
	v_cndmask_b32_e32 v79, v234, v79, vcc

; #define MFMA32(a, b, c) __builtin_amdgcn_mfma_f32_32x32x16_bf16((a), (b), (c), 0, 0, 0)
; template <int DQK, int MODE, bool QN, bool KN> ...
;     ...
;   auto compute = [&](int it, int bufi) {
;     const int kt = tile_of(it);
;     const int koff = (kt & 1) * 64;
;     const char* sK = smem + bufi * BUF + koff * KROW;
;     const char* sV = smem + bufi * BUF + KBYTES + koff * 64;
;     bool active = (MODE == 0) || (kt * 64 <= qwmax);
;     if (MODE == 2 && active) active = __builtin_amdgcn_ballot_w64(carry >= 1.17549435e-38f) != 0;
;     if (active) {
;       f32x16 sacc[2];
;       const float sinit = fixed_shift ? -sbound : 0.f;
; #pragma unroll
;       for (int kb = 0; kb < 2; ++kb) {
; #pragma unroll
;         for (int i = 0; i < 16; ++i) sacc[kb][i] = sinit;
; #pragma unroll
;         for (int s = 0; s < NS; ++s) {
;           const bf16x8 kf = *(const bf16x8*)(sK + (kb * 32 + r) * KROW + s * 32 + h * 16);
;           sacc[kb] = MFMA32(kf, qf[s], sacc[kb]);
;         }
;       }
;       const bool diag = (MODE != 0) && (kt * 64 + 63 >= q0 + wave * 32);
;       if (MODE != 0 && diag) {
; #pragma unroll
;         for (int kb = 0; kb < 2; ++kb)
; #pragma unroll
;           for (int i = 0; i < 16; ++i) {
;             const int key = kt * 64 + kb * 32 + (i & 3) + 8 * (i >> 2) + 4 * h;
;             if (MODE == 1 ? (key > qrow) : (key >= qrow)) sacc[kb][i] = -INFINITY;
;           }
;       }
.LBB0_1208:
	s_or_b64 exec, exec, s[2:3]
	s_add_i32 s2, s53, 0xffffff41
	v_cmp_le_i32_e32 vcc, s2, v243
	s_and_saveexec_b64 s[2:3], vcc
	s_cbranch_execz .LBB0_1218
	ds_read_b128 v[32:35], v251 offset:13312
	ds_read_b128 v[36:39], v251 offset:13344
	ds_read_b128 v[40:43], v251 offset:13376
	ds_read_b128 v[44:47], v251 offset:13408
	ds_read_b128 v[48:51], v251 offset:13440
	ds_read_b128 v[52:55], v251 offset:13472
	ds_read_b128 v[112:115], v251 offset:19968
	ds_read_b128 v[116:119], v251 offset:20000
	ds_read_b128 v[120:123], v251 offset:20032
	ds_read_b128 v[124:127], v251 offset:20064
	ds_read_b128 v[144:147], v251 offset:20096
	ds_read_b128 v[148:151], v251 offset:20128
	s_add_i32 s4, s53, 0xffffff80
	v_cmp_ge_i32_e32 vcc, s4, v236
	s_waitcnt lgkmcnt(11)
	v_mfma_f32_32x32x16_bf16 v[80:95], v[32:35], v[160:163], v[16:31]
	s_waitcnt lgkmcnt(10)
	v_mfma_f32_32x32x16_bf16 v[80:95], v[36:39], v[164:167], v[80:95]
	s_waitcnt lgkmcnt(9)
	v_mfma_f32_32x32x16_bf16 v[80:95], v[40:43], v[168:171], v[80:95]
	s_waitcnt lgkmcnt(8)
	v_mfma_f32_32x32x16_bf16 v[80:95], v[44:47], v[172:175], v[80:95]
	s_waitcnt lgkmcnt(7)
	v_mfma_f32_32x32x16_bf16 v[80:95], v[48:51], v[176:179], v[80:95]
	s_waitcnt lgkmcnt(6)
	v_mfma_f32_32x32x16_bf16 v[80:95], v[52:55], v[180:183], v[80:95]
	s_waitcnt lgkmcnt(5)
	v_mfma_f32_32x32x16_bf16 v[64:79], v[112:115], v[160:163], v[16:31]
	s_waitcnt lgkmcnt(4)
	v_mfma_f32_32x32x16_bf16 v[64:79], v[116:119], v[164:167], v[64:79]
	s_waitcnt lgkmcnt(3)
	v_mfma_f32_32x32x16_bf16 v[64:79], v[120:123], v[168:171], v[64:79]
	s_waitcnt lgkmcnt(2)
	v_mfma_f32_32x32x16_bf16 v[64:79], v[124:127], v[172:175], v[64:79]
	s_waitcnt lgkmcnt(1)
	v_mfma_f32_32x32x16_bf16 v[64:79], v[144:147], v[176:179], v[64:79]
	s_waitcnt lgkmcnt(0)
	v_mfma_f32_32x32x16_bf16 v[64:79], v[148:151], v[180:183], v[64:79]
	s_and_saveexec_b64 s[10:11], vcc
	s_cbranch_execz .LBB0_1211
	v_add_u32_e32 v0, s53, v247
	v_add_u32_e32 v14, 0xffffff41, v0
	v_cmp_le_i32_e32 vcc, v14, v237
	v_add_u32_e32 v14, 0xffffff42, v0
	s_nop 0
	v_cndmask_b32_e32 v80, v234, v80, vcc
	v_cmp_le_i32_e32 vcc, v14, v237
	v_add_u32_e32 v14, 0xffffff43, v0
	s_nop 0
	v_cndmask_b32_e32 v81, v234, v81, vcc
	v_cmp_le_i32_e32 vcc, v14, v237
	v_add_u32_e32 v14, 0xffffff44, v0
	s_nop 0
	v_cndmask_b32_e32 v82, v234, v82, vcc
	v_cmp_le_i32_e32 vcc, v14, v237
	v_add_u32_e32 v14, 0xffffff49, v0
	s_nop 0
	v_cndmask_b32_e32 v83, v234, v83, vcc
	v_cmp_le_i32_e32 vcc, v14, v237
	v_add_u32_e32 v14, 0xffffff4a, v0
	s_nop 0
	v_cndmask_b32_e32 v84, v234, v84, vcc
	v_cmp_le_i32_e32 vcc, v14, v237
	v_add_u32_e32 v14, 0xffffff4b, v0
	s_nop 0
	v_cndmask_b32_e32 v85, v234, v85, vcc
	v_cmp_le_i32_e32 vcc, v14, v237
	v_add_u32_e32 v14, 0xffffff4c, v0
	s_nop 0
	v_cndmask_b32_e32 v86, v234, v86, vcc
	v_cmp_le_i32_e32 vcc, v14, v237
	v_add_u32_e32 v14, 0xffffff51, v0
	s_nop 0
	v_cndmask_b32_e32 v87, v234, v87, vcc
	v_cmp_le_i32_e32 vcc, v14, v237
	v_add_u32_e32 v14, 0xffffff52, v0
	s_nop 0
	v_cndmask_b32_e32 v88, v234, v88, vcc
	v_cmp_le_i32_e32 vcc, v14, v237
	v_add_u32_e32 v14, 0xffffff53, v0
	s_nop 0
	v_cndmask_b32_e32 v89, v234, v89, vcc
	v_cmp_le_i32_e32 vcc, v14, v237
	v_add_u32_e32 v14, 0xffffff54, v0
	s_nop 0
	v_cndmask_b32_e32 v90, v234, v90, vcc
	v_cmp_le_i32_e32 vcc, v14, v237
	v_add_u32_e32 v14, 0xffffff59, v0
	s_nop 0
	v_cndmask_b32_e32 v91, v234, v91, vcc
	v_cmp_le_i32_e32 vcc, v14, v237
	v_add_u32_e32 v14, 0xffffff5a, v0
	s_nop 0
	v_cndmask_b32_e32 v92, v234, v92, vcc
	v_cmp_le_i32_e32 vcc, v14, v237
	v_add_u32_e32 v14, 0xffffff5b, v0
	s_nop 0
	v_cndmask_b32_e32 v93, v234, v93, vcc
	v_cmp_le_i32_e32 vcc, v14, v237
	v_add_u32_e32 v14, 0xffffff5c, v0
	s_nop 0
	v_cndmask_b32_e32 v94, v234, v94, vcc
	v_cmp_le_i32_e32 vcc, v14, v237
	v_add_u32_e32 v14, 0xffffff61, v0
	s_nop 0
	v_cndmask_b32_e32 v95, v234, v95, vcc
	v_cmp_le_i32_e32 vcc, v14, v237
	v_add_u32_e32 v14, 0xffffff62, v0
	s_nop 0
	v_cndmask_b32_e32 v64, v234, v64, vcc
	v_cmp_le_i32_e32 vcc, v14, v237
	v_add_u32_e32 v14, 0xffffff63, v0
	s_nop 0
	v_cndmask_b32_e32 v65, v234, v65, vcc
	v_cmp_le_i32_e32 vcc, v14, v237
	v_add_u32_e32 v14, 0xffffff64, v0
	s_nop 0
	v_cndmask_b32_e32 v66, v234, v66, vcc
	v_cmp_le_i32_e32 vcc, v14, v237
	v_add_u32_e32 v14, 0xffffff69, v0
	s_nop 0
	v_cndmask_b32_e32 v67, v234, v67, vcc
	v_cmp_le_i32_e32 vcc, v14, v237
	v_add_u32_e32 v14, 0xffffff6a, v0
	s_nop 0
	v_cndmask_b32_e32 v68, v234, v68, vcc
	v_cmp_le_i32_e32 vcc, v14, v237
	v_add_u32_e32 v14, 0xffffff6b, v0
	s_nop 0
	v_cndmask_b32_e32 v69, v234, v69, vcc
	v_cmp_le_i32_e32 vcc, v14, v237
	v_add_u32_e32 v14, 0xffffff6c, v0
	s_nop 0
	v_cndmask_b32_e32 v70, v234, v70, vcc
	v_cmp_le_i32_e32 vcc, v14, v237
	v_add_u32_e32 v14, 0xffffff71, v0
	s_nop 0
	v_cndmask_b32_e32 v71, v234, v71, vcc
	v_cmp_le_i32_e32 vcc, v14, v237
	v_add_u32_e32 v14, 0xffffff72, v0
	s_nop 0
	v_cndmask_b32_e32 v72, v234, v72, vcc
	v_cmp_le_i32_e32 vcc, v14, v237
	v_add_u32_e32 v14, 0xffffff73, v0
	s_nop 0
	v_cndmask_b32_e32 v73, v234, v73, vcc
	v_cmp_le_i32_e32 vcc, v14, v237
	v_add_u32_e32 v14, 0xffffff74, v0
	s_nop 0
	v_cndmask_b32_e32 v74, v234, v74, vcc
	v_cmp_le_i32_e32 vcc, v14, v237
	v_add_u32_e32 v14, 0xffffff79, v0
	s_nop 0
	v_cndmask_b32_e32 v75, v234, v75, vcc
	v_cmp_le_i32_e32 vcc, v14, v237
	v_add_u32_e32 v14, 0xffffff7a, v0
	s_nop 0
	v_cndmask_b32_e32 v76, v234, v76, vcc
	v_cmp_le_i32_e32 vcc, v14, v237
	v_add_u32_e32 v14, 0xffffff7b, v0
	v_add_u32_e32 v0, 0xffffff7c, v0
	v_cndmask_b32_e32 v77, v234, v77, vcc
	v_cmp_le_i32_e32 vcc, v14, v237
	s_nop 1
	v_cndmask_b32_e32 v78, v234, v78, vcc
	v_cmp_le_i32_e32 vcc, v0, v237
	s_nop 1
	v_cndmask_b32_e32 v79, v234, v79, vcc

; #define MFMA32(a, b, c) __builtin_amdgcn_mfma_f32_32x32x16_bf16((a), (b), (c), 0, 0, 0)
; #define AT_SB __builtin_amdgcn_sched_barrier(0);
; template <int DQK, int MODE, bool QN, bool KN> ...
;     ...
;   auto compute = [&](int it, int bufi) {
;     const int kt = tile_of(it);
;     const int koff = (kt & 1) * 64;
;     const char* sK = smem + bufi * BUF + koff * KROW;
;     const char* sV = smem + bufi * BUF + KBYTES + koff * 64;
;     bool active = (MODE == 0) || (kt * 64 <= qwmax);
;     if (MODE == 2 && active) active = __builtin_amdgcn_ballot_w64(carry >= 1.17549435e-38f) != 0;
;     if (active) {
;       f32x16 sacc[2];
;       const float sinit = fixed_shift ? -sbound : 0.f;
; #pragma unroll
;       for (int kb = 0; kb < 2; ++kb) {
; #pragma unroll
;         for (int i = 0; i < 16; ++i) sacc[kb][i] = sinit;
; #pragma unroll
;         for (int s = 0; s < NS; ++s) {
;           const bf16x8 kf = *(const bf16x8*)(sK + (kb * 32 + r) * KROW + s * 32 + h * 16);
;           sacc[kb] = MFMA32(kf, qf[s], sacc[kb]);
;         }
;       }
;       const bool diag = (MODE != 0) && (kt * 64 + 63 >= q0 + wave * 32);
;       if (MODE != 0 && diag) {
; #pragma unroll
;         for (int kb = 0; kb < 2; ++kb)
; #pragma unroll
;           for (int i = 0; i < 16; ++i) {
;             const int key = kt * 64 + kb * 32 + (i & 3) + 8 * (i >> 2) + 4 * h;
;             if (MODE == 1 ? (key > qrow) : (key >= qrow)) sacc[kb][i] = -INFINITY;
;           }
;       }
;     ...
;     AT_SWRITE(rk1, rv1, 1)
;     if (MODE == 2) { if (__syncthreads_and(carry < 1.17549435e-38f)) break; } else { __syncthreads(); }
;     AT_SB AT_GLOAD(rk1, rv1, sg + 3)
;     AT_SB compute(2 * sg + 2, 1); compute(2 * sg + 3, 1); AT_SB
.LBB0_1218:
	s_or_b64 exec, exec, s[2:3]
	s_waitcnt vmcnt(9)
	ds_write_b128 v244, v[184:187] offset:43008
	s_waitcnt vmcnt(8)
	ds_write_b128 v245, v[188:191] offset:43008
	s_waitcnt vmcnt(7)
	ds_write_b128 v246, v[192:195] offset:43008
	s_waitcnt vmcnt(6)
	ds_write_b128 v250, v[196:199]
	s_waitcnt vmcnt(5)
	ds_write_b128 v250, v[200:203] offset:4096
	s_waitcnt lgkmcnt(0)
	s_barrier
	s_min_i32 s2, s45, s13
	s_lshl_b32 s4, s2, 7
	v_add_u32_e32 v0, s4, v238
	v_mad_i64_i32 v[14:15], s[2:3], v0, s36, v[220:221]
	v_add_u32_e32 v0, s4, v239
	v_mad_i64_i32 v[64:65], s[2:3], v0, s36, v[222:223]
	v_add_u32_e32 v0, s4, v240
	global_load_dwordx4 v[184:187], v[14:15], off
	global_load_dwordx4 v[188:191], v[64:65], off
	v_mad_i64_i32 v[14:15], s[2:3], v0, s36, v[224:225]
	v_add_u32_e32 v0, s4, v241
	v_mad_i64_i32 v[64:65], s[2:3], v0, s37, v[218:219]
	v_add_u32_e32 v0, s4, v242
	global_load_dwordx4 v[192:195], v[14:15], off
	global_load_dwordx4 v[196:199], v[64:65], off
	v_mad_i64_i32 v[14:15], s[2:3], v0, s37, v[218:219]
	global_load_dwordx4 v[200:203], v[14:15], off
	s_add_i32 s2, s53, 0xffffff81
	v_cmp_le_i32_e32 vcc, s2, v243
	s_and_saveexec_b64 s[2:3], vcc
	s_cbranch_execz .LBB0_1228
	ds_read_b128 v[32:35], v251 offset:43008
	ds_read_b128 v[36:39], v251 offset:43040
	ds_read_b128 v[40:43], v251 offset:43072
	ds_read_b128 v[44:47], v251 offset:43104
	ds_read_b128 v[48:51], v251 offset:43136
	ds_read_b128 v[52:55], v251 offset:43168
	ds_read_b128 v[112:115], v251 offset:49664
	ds_read_b128 v[116:119], v251 offset:49696
	ds_read_b128 v[120:123], v251 offset:49728
	ds_read_b128 v[124:127], v251 offset:49760
	ds_read_b128 v[144:147], v251 offset:49792
	ds_read_b128 v[148:151], v251 offset:49824
	s_sub_i32 s4, s53, 64
	v_cmp_ge_i32_e32 vcc, s4, v236
	s_waitcnt lgkmcnt(11)
	v_mfma_f32_32x32x16_bf16 v[80:95], v[32:35], v[160:163], v[16:31]
	s_waitcnt lgkmcnt(10)
	v_mfma_f32_32x32x16_bf16 v[80:95], v[36:39], v[164:167], v[80:95]
	s_waitcnt lgkmcnt(9)
	v_mfma_f32_32x32x16_bf16 v[80:95], v[40:43], v[168:171], v[80:95]
	s_waitcnt lgkmcnt(8)
	v_mfma_f32_32x32x16_bf16 v[80:95], v[44:47], v[172:175], v[80:95]
	s_waitcnt lgkmcnt(7)
	v_mfma_f32_32x32x16_bf16 v[80:95], v[48:51], v[176:179], v[80:95]
	s_waitcnt lgkmcnt(6)
	v_mfma_f32_32x32x16_bf16 v[80:95], v[52:55], v[180:183], v[80:95]
	s_waitcnt lgkmcnt(5)
	v_mfma_f32_32x32x16_bf16 v[64:79], v[112:115], v[160:163], v[16:31]
	s_waitcnt lgkmcnt(4)
	v_mfma_f32_32x32x16_bf16 v[64:79], v[116:119], v[164:167], v[64:79]
	s_waitcnt lgkmcnt(3)
	v_mfma_f32_32x32x16_bf16 v[64:79], v[120:123], v[168:171], v[64:79]
	s_waitcnt lgkmcnt(2)
	v_mfma_f32_32x32x16_bf16 v[64:79], v[124:127], v[172:175], v[64:79]
	s_waitcnt lgkmcnt(1)
	v_mfma_f32_32x32x16_bf16 v[64:79], v[144:147], v[176:179], v[64:79]
	s_waitcnt lgkmcnt(0)
	v_mfma_f32_32x32x16_bf16 v[64:79], v[148:151], v[180:183], v[64:79]
	s_and_saveexec_b64 s[10:11], vcc
	s_cbranch_execz .LBB0_1221
	v_add_u32_e32 v0, s53, v247
	v_add_u32_e32 v14, 0xffffff81, v0
	v_cmp_le_i32_e32 vcc, v14, v237
	v_add_u32_e32 v14, 0xffffff82, v0
	s_nop 0
	v_cndmask_b32_e32 v80, v234, v80, vcc
	v_cmp_le_i32_e32 vcc, v14, v237
	v_add_u32_e32 v14, 0xffffff83, v0
	s_nop 0
	v_cndmask_b32_e32 v81, v234, v81, vcc
	v_cmp_le_i32_e32 vcc, v14, v237
	v_add_u32_e32 v14, 0xffffff84, v0
	s_nop 0
	v_cndmask_b32_e32 v82, v234, v82, vcc
	v_cmp_le_i32_e32 vcc, v14, v237
	v_add_u32_e32 v14, 0xffffff89, v0
	s_nop 0
	v_cndmask_b32_e32 v83, v234, v83, vcc
	v_cmp_le_i32_e32 vcc, v14, v237
	v_add_u32_e32 v14, 0xffffff8a, v0
	s_nop 0
	v_cndmask_b32_e32 v84, v234, v84, vcc
	v_cmp_le_i32_e32 vcc, v14, v237
	v_add_u32_e32 v14, 0xffffff8b, v0
	s_nop 0
	v_cndmask_b32_e32 v85, v234, v85, vcc
	v_cmp_le_i32_e32 vcc, v14, v237
	v_add_u32_e32 v14, 0xffffff8c, v0
	s_nop 0
	v_cndmask_b32_e32 v86, v234, v86, vcc
	v_cmp_le_i32_e32 vcc, v14, v237
	v_add_u32_e32 v14, 0xffffff91, v0
	s_nop 0
	v_cndmask_b32_e32 v87, v234, v87, vcc
	v_cmp_le_i32_e32 vcc, v14, v237
	v_add_u32_e32 v14, 0xffffff92, v0
	s_nop 0
	v_cndmask_b32_e32 v88, v234, v88, vcc
	v_cmp_le_i32_e32 vcc, v14, v237
	v_add_u32_e32 v14, 0xffffff93, v0
	s_nop 0
	v_cndmask_b32_e32 v89, v234, v89, vcc
	v_cmp_le_i32_e32 vcc, v14, v237
	v_add_u32_e32 v14, 0xffffff94, v0
	s_nop 0
	v_cndmask_b32_e32 v90, v234, v90, vcc
	v_cmp_le_i32_e32 vcc, v14, v237
	v_add_u32_e32 v14, 0xffffff99, v0
	s_nop 0
	v_cndmask_b32_e32 v91, v234, v91, vcc
	v_cmp_le_i32_e32 vcc, v14, v237
	v_add_u32_e32 v14, 0xffffff9a, v0
	s_nop 0
	v_cndmask_b32_e32 v92, v234, v92, vcc
	v_cmp_le_i32_e32 vcc, v14, v237
	v_add_u32_e32 v14, 0xffffff9b, v0
	s_nop 0
	v_cndmask_b32_e32 v93, v234, v93, vcc
	v_cmp_le_i32_e32 vcc, v14, v237
	v_add_u32_e32 v14, 0xffffff9c, v0
	s_nop 0
	v_cndmask_b32_e32 v94, v234, v94, vcc
	v_cmp_le_i32_e32 vcc, v14, v237
	v_add_u32_e32 v14, 0xffffffa1, v0
	s_nop 0
	v_cndmask_b32_e32 v95, v234, v95, vcc
	v_cmp_le_i32_e32 vcc, v14, v237
	v_add_u32_e32 v14, 0xffffffa2, v0
	s_nop 0
	v_cndmask_b32_e32 v64, v234, v64, vcc
	v_cmp_le_i32_e32 vcc, v14, v237
	v_add_u32_e32 v14, 0xffffffa3, v0
	s_nop 0
	v_cndmask_b32_e32 v65, v234, v65, vcc
	v_cmp_le_i32_e32 vcc, v14, v237
	v_add_u32_e32 v14, 0xffffffa4, v0
	s_nop 0
	v_cndmask_b32_e32 v66, v234, v66, vcc
	v_cmp_le_i32_e32 vcc, v14, v237
	v_add_u32_e32 v14, 0xffffffa9, v0
	s_nop 0
	v_cndmask_b32_e32 v67, v234, v67, vcc
	v_cmp_le_i32_e32 vcc, v14, v237
	v_add_u32_e32 v14, 0xffffffaa, v0
	s_nop 0
	v_cndmask_b32_e32 v68, v234, v68, vcc
	v_cmp_le_i32_e32 vcc, v14, v237
	v_add_u32_e32 v14, 0xffffffab, v0
	s_nop 0
	v_cndmask_b32_e32 v69, v234, v69, vcc
	v_cmp_le_i32_e32 vcc, v14, v237
	v_add_u32_e32 v14, 0xffffffac, v0
	s_nop 0
	v_cndmask_b32_e32 v70, v234, v70, vcc
	v_cmp_le_i32_e32 vcc, v14, v237
	v_add_u32_e32 v14, 0xffffffb1, v0
	s_nop 0
	v_cndmask_b32_e32 v71, v234, v71, vcc
	v_cmp_le_i32_e32 vcc, v14, v237
	v_add_u32_e32 v14, 0xffffffb2, v0
	s_nop 0
	v_cndmask_b32_e32 v72, v234, v72, vcc
	v_cmp_le_i32_e32 vcc, v14, v237
	v_add_u32_e32 v14, 0xffffffb3, v0
	s_nop 0
	v_cndmask_b32_e32 v73, v234, v73, vcc
	v_cmp_le_i32_e32 vcc, v14, v237
	v_add_u32_e32 v14, 0xffffffb4, v0
	s_nop 0
	v_cndmask_b32_e32 v74, v234, v74, vcc
	v_cmp_le_i32_e32 vcc, v14, v237
	v_add_u32_e32 v14, 0xffffffb9, v0
	s_nop 0
	v_cndmask_b32_e32 v75, v234, v75, vcc
	v_cmp_le_i32_e32 vcc, v14, v237
	v_add_u32_e32 v14, 0xffffffba, v0
	s_nop 0
	v_cndmask_b32_e32 v76, v234, v76, vcc
	v_cmp_le_i32_e32 vcc, v14, v237
	v_add_u32_e32 v14, 0xffffffbb, v0
	v_add_u32_e32 v0, 0xffffffbc, v0
	v_cndmask_b32_e32 v77, v234, v77, vcc
	v_cmp_le_i32_e32 vcc, v14, v237
	s_nop 1
	v_cndmask_b32_e32 v78, v234, v78, vcc
	v_cmp_le_i32_e32 vcc, v0, v237
	s_nop 1
	v_cndmask_b32_e32 v79, v234, v79, vcc

; #define MFMA32(a, b, c) __builtin_amdgcn_mfma_f32_32x32x16_bf16((a), (b), (c), 0, 0, 0)
; template <int DQK, int MODE, bool QN, bool KN> ...
;     ...
;   auto compute = [&](int it, int bufi) {
;     const int kt = tile_of(it);
;     const int koff = (kt & 1) * 64;
;     const char* sK = smem + bufi * BUF + koff * KROW;
;     const char* sV = smem + bufi * BUF + KBYTES + koff * 64;
;     bool active = (MODE == 0) || (kt * 64 <= qwmax);
;     if (MODE == 2 && active) active = __builtin_amdgcn_ballot_w64(carry >= 1.17549435e-38f) != 0;
;     if (active) {
;       f32x16 sacc[2];
;       const float sinit = fixed_shift ? -sbound : 0.f;
; #pragma unroll
;       for (int kb = 0; kb < 2; ++kb) {
; #pragma unroll
;         for (int i = 0; i < 16; ++i) sacc[kb][i] = sinit;
; #pragma unroll
;         for (int s = 0; s < NS; ++s) {
;           const bf16x8 kf = *(const bf16x8*)(sK + (kb * 32 + r) * KROW + s * 32 + h * 16);
;           sacc[kb] = MFMA32(kf, qf[s], sacc[kb]);
;         }
;       }
;       const bool diag = (MODE != 0) && (kt * 64 + 63 >= q0 + wave * 32);
;       if (MODE != 0 && diag) {
; #pragma unroll
;         for (int kb = 0; kb < 2; ++kb)
; #pragma unroll
;           for (int i = 0; i < 16; ++i) {
;             const int key = kt * 64 + kb * 32 + (i & 3) + 8 * (i >> 2) + 4 * h;
;             if (MODE == 1 ? (key > qrow) : (key >= qrow)) sacc[kb][i] = -INFINITY;
;           }
;       }
.LBB0_1228:
	s_or_b64 exec, exec, s[2:3]
	s_sub_i32 s2, s53, 63
	v_cmp_le_i32_e32 vcc, s2, v243
	s_and_saveexec_b64 s[2:3], vcc
	s_cbranch_execz .LBB0_1197
	ds_read_b128 v[32:35], v251 offset:56320
	ds_read_b128 v[36:39], v251 offset:56352
	ds_read_b128 v[40:43], v251 offset:56384
	ds_read_b128 v[44:47], v251 offset:56416
	ds_read_b128 v[48:51], v251 offset:56448
	ds_read_b128 v[52:55], v251 offset:56480
	ds_read_b128 v[112:115], v251 offset:62976
	ds_read_b128 v[116:119], v251 offset:63008
	ds_read_b128 v[120:123], v251 offset:63040
	ds_read_b128 v[124:127], v251 offset:63072
	ds_read_b128 v[144:147], v251 offset:63104
	ds_read_b128 v[148:151], v251 offset:63136
	v_cmp_ge_i32_e32 vcc, s53, v236
	s_waitcnt lgkmcnt(11)
	v_mfma_f32_32x32x16_bf16 v[80:95], v[32:35], v[160:163], v[16:31]
	s_waitcnt lgkmcnt(10)
	v_mfma_f32_32x32x16_bf16 v[80:95], v[36:39], v[164:167], v[80:95]
	s_waitcnt lgkmcnt(9)
	v_mfma_f32_32x32x16_bf16 v[80:95], v[40:43], v[168:171], v[80:95]
	s_waitcnt lgkmcnt(8)
	v_mfma_f32_32x32x16_bf16 v[80:95], v[44:47], v[172:175], v[80:95]
	s_waitcnt lgkmcnt(7)
	v_mfma_f32_32x32x16_bf16 v[80:95], v[48:51], v[176:179], v[80:95]
	s_waitcnt lgkmcnt(6)
	v_mfma_f32_32x32x16_bf16 v[80:95], v[52:55], v[180:183], v[80:95]
	s_waitcnt lgkmcnt(5)
	v_mfma_f32_32x32x16_bf16 v[64:79], v[112:115], v[160:163], v[16:31]
	s_waitcnt lgkmcnt(4)
	v_mfma_f32_32x32x16_bf16 v[64:79], v[116:119], v[164:167], v[64:79]
	s_waitcnt lgkmcnt(3)
	v_mfma_f32_32x32x16_bf16 v[64:79], v[120:123], v[168:171], v[64:79]
	s_waitcnt lgkmcnt(2)
	v_mfma_f32_32x32x16_bf16 v[64:79], v[124:127], v[172:175], v[64:79]
	s_waitcnt lgkmcnt(1)
	v_mfma_f32_32x32x16_bf16 v[64:79], v[144:147], v[176:179], v[64:79]
	s_waitcnt lgkmcnt(0)
	v_mfma_f32_32x32x16_bf16 v[64:79], v[148:151], v[180:183], v[64:79]
	s_and_saveexec_b64 s[10:11], vcc
	s_cbranch_execz .LBB0_1231
	v_add_u32_e32 v0, s53, v247
	v_subrev_u32_e32 v14, 63, v0
	v_cmp_le_i32_e32 vcc, v14, v237
	v_subrev_u32_e32 v14, 62, v0
	s_nop 0
	v_cndmask_b32_e32 v80, v234, v80, vcc
	v_cmp_le_i32_e32 vcc, v14, v237
	v_subrev_u32_e32 v14, 61, v0
	s_nop 0
	v_cndmask_b32_e32 v81, v234, v81, vcc
	v_cmp_le_i32_e32 vcc, v14, v237
	v_subrev_u32_e32 v14, 60, v0
	s_nop 0
	v_cndmask_b32_e32 v82, v234, v82, vcc
	v_cmp_le_i32_e32 vcc, v14, v237
	v_subrev_u32_e32 v14, 55, v0
	s_nop 0
	v_cndmask_b32_e32 v83, v234, v83, vcc
	v_cmp_le_i32_e32 vcc, v14, v237
	v_subrev_u32_e32 v14, 54, v0
	s_nop 0
	v_cndmask_b32_e32 v84, v234, v84, vcc
	v_cmp_le_i32_e32 vcc, v14, v237
	v_subrev_u32_e32 v14, 53, v0
	s_nop 0
	v_cndmask_b32_e32 v85, v234, v85, vcc
	v_cmp_le_i32_e32 vcc, v14, v237
	v_subrev_u32_e32 v14, 52, v0
	s_nop 0
	v_cndmask_b32_e32 v86, v234, v86, vcc
	v_cmp_le_i32_e32 vcc, v14, v237
	v_subrev_u32_e32 v14, 47, v0
	s_nop 0
	v_cndmask_b32_e32 v87, v234, v87, vcc
	v_cmp_le_i32_e32 vcc, v14, v237
	v_subrev_u32_e32 v14, 46, v0
	s_nop 0
	v_cndmask_b32_e32 v88, v234, v88, vcc
	v_cmp_le_i32_e32 vcc, v14, v237
	v_subrev_u32_e32 v14, 45, v0
	s_nop 0
	v_cndmask_b32_e32 v89, v234, v89, vcc
	v_cmp_le_i32_e32 vcc, v14, v237
	v_subrev_u32_e32 v14, 44, v0
	s_nop 0
	v_cndmask_b32_e32 v90, v234, v90, vcc
	v_cmp_le_i32_e32 vcc, v14, v237
	v_subrev_u32_e32 v14, 39, v0
	s_nop 0
	v_cndmask_b32_e32 v91, v234, v91, vcc
	v_cmp_le_i32_e32 vcc, v14, v237
	v_subrev_u32_e32 v14, 38, v0
	s_nop 0
	v_cndmask_b32_e32 v92, v234, v92, vcc
	v_cmp_le_i32_e32 vcc, v14, v237
	v_subrev_u32_e32 v14, 37, v0
	s_nop 0
	v_cndmask_b32_e32 v93, v234, v93, vcc
	v_cmp_le_i32_e32 vcc, v14, v237
	v_subrev_u32_e32 v14, 36, v0
	s_nop 0
	v_cndmask_b32_e32 v94, v234, v94, vcc
	v_cmp_le_i32_e32 vcc, v14, v237
	v_subrev_u32_e32 v14, 31, v0
	s_nop 0
	v_cndmask_b32_e32 v95, v234, v95, vcc
	v_cmp_le_i32_e32 vcc, v14, v237
	v_subrev_u32_e32 v14, 30, v0
	s_nop 0
	v_cndmask_b32_e32 v64, v234, v64, vcc
	v_cmp_le_i32_e32 vcc, v14, v237
	v_subrev_u32_e32 v14, 29, v0
	s_nop 0
	v_cndmask_b32_e32 v65, v234, v65, vcc
	v_cmp_le_i32_e32 vcc, v14, v237
	v_subrev_u32_e32 v14, 28, v0
	s_nop 0
	v_cndmask_b32_e32 v66, v234, v66, vcc
	v_cmp_le_i32_e32 vcc, v14, v237
	v_subrev_u32_e32 v14, 23, v0
	s_nop 0
	v_cndmask_b32_e32 v67, v234, v67, vcc
	v_cmp_le_i32_e32 vcc, v14, v237
	v_subrev_u32_e32 v14, 22, v0
	s_nop 0
	v_cndmask_b32_e32 v68, v234, v68, vcc
	v_cmp_le_i32_e32 vcc, v14, v237
	v_subrev_u32_e32 v14, 21, v0
	s_nop 0
	v_cndmask_b32_e32 v69, v234, v69, vcc
	v_cmp_le_i32_e32 vcc, v14, v237
	v_subrev_u32_e32 v14, 20, v0
	s_nop 0
	v_cndmask_b32_e32 v70, v234, v70, vcc
	v_cmp_le_i32_e32 vcc, v14, v237
	v_add_u32_e32 v14, -15, v0
	s_nop 0
	v_cndmask_b32_e32 v71, v234, v71, vcc
	v_cmp_le_i32_e32 vcc, v14, v237
	v_add_u32_e32 v14, -14, v0
	s_nop 0
	v_cndmask_b32_e32 v72, v234, v72, vcc
	v_cmp_le_i32_e32 vcc, v14, v237
	v_add_u32_e32 v14, -13, v0
	s_nop 0
	v_cndmask_b32_e32 v73, v234, v73, vcc
	v_cmp_le_i32_e32 vcc, v14, v237
	v_add_u32_e32 v14, -12, v0
	s_nop 0
	v_cndmask_b32_e32 v74, v234, v74, vcc
	v_cmp_le_i32_e32 vcc, v14, v237
	v_add_u32_e32 v14, -7, v0
	s_nop 0
	v_cndmask_b32_e32 v75, v234, v75, vcc
	v_cmp_le_i32_e32 vcc, v14, v237
	v_add_u32_e32 v14, -6, v0
	s_nop 0
	v_cndmask_b32_e32 v76, v234, v76, vcc
	v_cmp_le_i32_e32 vcc, v14, v237
	v_add_u32_e32 v14, -5, v0
	v_add_u32_e32 v0, -4, v0
	v_cndmask_b32_e32 v77, v234, v77, vcc
	v_cmp_le_i32_e32 vcc, v14, v237
	s_nop 1
	v_cndmask_b32_e32 v78, v234, v78, vcc
	v_cmp_le_i32_e32 vcc, v0, v237
	s_nop 1
	v_cndmask_b32_e32 v79, v234, v79, vcc
